# dil_tile and reta_tile LDS staging hand-rescheduled (row loads issued together instead of serialized); attention items streamed; rmsnorm phases
# speedup vs baseline: 1.0462x; 1.0026x over previous
.LBB0_731:
	s_andn2_b64 vcc, exec, s[2:3]
	s_cbranch_vccnz .LBB0_733
	s_and_b32 s4, s56, 7
	v_cvt_f32_ubyte0_e32 v0, s4
	v_sub_f32_e32 v0, 0xc0a00000, v0
	s_mov_b32 s3, 0xc2fc0000
	v_cmp_gt_f32_e32 vcc, s3, v0
	s_add_i32 s2, s56, 0xfffffd00
	s_and_b64 s[6:7], vcc, exec
	v_cndmask_b32_e32 v1, 0, v225, vcc
	v_add_f32_e32 v0, v0, v1
	v_exp_f32_e32 v0, v0
	s_cselect_b32 s3, 0xffffffc0, 0
	v_mov_b32_e32 v73, v208
	v_ldexp_f32 v16, v0, s3
	v_sub_f32_e32 v2, 1.0, v16
	v_add_f32_e32 v0, -1.0, v2
	v_sub_f32_e32 v1, v0, v2
	v_add_f32_e32 v1, 1.0, v1
	v_sub_f32_e64 v0, -v16, v0
	v_add_f32_e32 v3, v0, v1
	v_frexp_mant_f32_e32 v0, v2
	s_mov_b32 s3, 0x3f2aaaab
	v_cmp_gt_f32_e32 vcc, s3, v0
	v_cvt_f64_f32_e32 v[0:1], v2
	v_frexp_exp_i32_f64_e32 v0, v[0:1]
	v_subbrev_co_u32_e32 v8, vcc, 0, v0, vcc
	v_sub_u32_e32 v0, 0, v8
	v_ldexp_f32 v1, v2, v0
	v_add_f32_e32 v2, -1.0, v1
	v_add_f32_e32 v4, 1.0, v1
	v_ldexp_f32 v0, v3, v0
	v_add_f32_e32 v3, 1.0, v2
	v_add_f32_e32 v5, -1.0, v4
	v_sub_f32_e32 v3, v1, v3
	v_sub_f32_e32 v1, v1, v5
	v_add_f32_e32 v3, v0, v3
	v_add_f32_e32 v0, v0, v1
	v_add_f32_e32 v9, v4, v0
	v_rcp_f32_e32 v11, v9
	v_sub_f32_e32 v1, v9, v4
	v_sub_f32_e32 v10, v0, v1
	v_add_f32_e32 v1, v2, v3
	v_mul_f32_e32 v13, v1, v11
	v_sub_f32_e32 v0, v1, v2
	v_mul_f32_e32 v2, v9, v13
	v_fma_f32 v4, v13, v9, -v2
	v_fmac_f32_e32 v4, v13, v10
	v_sub_f32_e32 v12, v3, v0
	v_add_f32_e32 v0, v2, v4
	v_sub_f32_e32 v3, v1, v0
	v_pk_add_f32 v[6:7], v[0:1], v[2:3] neg_lo:[0,1] neg_hi:[0,1]
	v_mov_b32_e32 v5, v0
	v_pk_add_f32 v[0:1], v[6:7], v[4:5] neg_lo:[0,1] neg_hi:[0,1]
	s_mov_b32 s3, 0x3f317218
	v_add_f32_e32 v1, v12, v1
	v_add_f32_e32 v0, v0, v1
	v_add_f32_e32 v1, v3, v0
	v_mul_f32_e32 v12, v11, v1
	v_mul_f32_e32 v2, v9, v12
	v_fma_f32 v4, v12, v9, -v2
	v_fmac_f32_e32 v4, v12, v10
	v_sub_f32_e32 v3, v3, v1
	v_add_f32_e32 v9, v0, v3
	v_add_f32_e32 v0, v2, v4
	v_sub_f32_e32 v3, v1, v0
	v_pk_add_f32 v[6:7], v[0:1], v[2:3] neg_lo:[0,1] neg_hi:[0,1]
	v_mov_b32_e32 v5, v0
	v_pk_add_f32 v[0:1], v[6:7], v[4:5] neg_lo:[0,1] neg_hi:[0,1]
	v_cmp_nlt_f32_e32 vcc, 1.0, v16
	v_add_f32_e32 v1, v9, v1
	v_add_f32_e32 v0, v0, v1
	v_add_f32_e32 v1, v13, v12
	v_add_f32_e32 v0, v3, v0
	v_sub_f32_e32 v2, v1, v13
	v_mul_f32_e32 v0, v11, v0
	v_sub_f32_e32 v2, v12, v2
	v_add_f32_e32 v2, v2, v0
	v_add_f32_e32 v4, v1, v2
	v_mul_f32_e32 v5, v4, v4
	v_fmamk_f32 v0, v5, 0x3e9b6dac, v196
	v_fmaak_f32 v181, v5, v0, 0x3f2aaada
	v_cvt_f32_i32_e32 v0, v8
	v_sub_f32_e32 v1, v4, v1
	v_sub_f32_e32 v1, v2, v1
	v_ldexp_f32 v6, v1, 1
	v_mul_f32_e32 v1, v4, v5
	v_ldexp_f32 v3, v4, 1
	v_pk_mul_f32 v[4:5], v[0:1], v[180:181]
	v_and_b32_e32 v72, 31, v73
	v_fma_f32 v2, v0, s3, -v4
	v_fmac_f32_e32 v2, 0xb102e308, v0
	v_pk_add_f32 v[0:1], v[4:5], v[2:3]
	s_mov_b32 s3, 0x33800000
	v_sub_f32_e32 v3, v1, v3
	v_sub_f32_e32 v3, v5, v3
	v_add_f32_e32 v7, v6, v3
	v_mov_b32_e32 v6, v4
	v_pk_add_f32 v[4:5], v[0:1], v[4:5] neg_lo:[0,1] neg_hi:[0,1]
	v_pk_add_f32 v[8:9], v[0:1], v[6:7]
	v_mov_b32_e32 v3, v0
	v_mov_b32_e32 v5, v9
	v_pk_add_f32 v[10:11], v[2:3], v[4:5] neg_lo:[0,1] neg_hi:[0,1]
	v_pk_add_f32 v[2:3], v[2:3], v[4:5]
	v_mov_b32_e32 v14, v1
	v_pk_add_f32 v[4:5], v[2:3], v[0:1] op_sel:[1,0] op_sel_hi:[0,1] neg_lo:[0,1] neg_hi:[0,1]
	v_pk_add_f32 v[12:13], v[8:9], v[4:5] op_sel_hi:[1,0] neg_lo:[0,1] neg_hi:[0,1]
	v_mov_b32_e32 v8, v9
	v_mov_b32_e32 v9, v3
	v_mov_b32_e32 v15, v4
	v_pk_add_f32 v[4:5], v[8:9], v[14:15] neg_lo:[0,1] neg_hi:[0,1]
	v_mov_b32_e32 v6, v7
	v_mov_b32_e32 v7, v0
	v_pk_add_f32 v[0:1], v[6:7], v[4:5] neg_lo:[0,1] neg_hi:[0,1]
	v_mov_b32_e32 v12, v10
	v_pk_add_f32 v[4:5], v[12:13], v[0:1]
	v_mov_b32_e32 v11, v3
	v_pk_add_f32 v[6:7], v[4:5], v[4:5] op_sel:[0,1] op_sel_hi:[1,0]
	v_ashrrev_i32_e32 v12, 4, v73
	v_pk_add_f32 v[2:3], v[2:3], v[6:7] op_sel:[1,0] op_sel_hi:[0,1]
	v_mov_b32_e32 v5, v2
	v_pk_add_f32 v[8:9], v[4:5], v[10:11] neg_lo:[0,1] neg_hi:[0,1]
	v_mov_b32_e32 v1, v6
	v_sub_f32_e32 v3, v4, v8
	v_pk_add_f32 v[0:1], v[0:1], v[8:9] neg_lo:[0,1] neg_hi:[0,1]
	v_sub_f32_e32 v3, v10, v3
	v_add_f32_e32 v0, v0, v3
	v_add_f32_e32 v0, v0, v1
	v_add_f32_e32 v0, v2, v0
	v_cndmask_b32_e32 v0, v226, v0, vcc
	v_cmp_neq_f32_e32 vcc, 1.0, v16
	v_mov_b64_e32 v[4:5], s[0:1]
	v_sub_u32_e32 v8, 0x7f, v12
	v_cndmask_b32_e32 v0, v227, v0, vcc
	v_cmp_gt_f32_e32 vcc, s3, v16
	s_lshl_b32 s3, s2, 4
	s_and_b32 s5, s3, 0x1f80
	v_cndmask_b32_e64 v7, v0, -v16, vcc
	s_lshl_b32 s2, s2, 16
	v_readlane_b32 s3, v252, 50
	v_lshlrev_b32_e32 v0, 4, v73
	s_add_u32 s2, s3, s2
	v_readlane_b32 s3, v252, 51
	v_and_b32_e32 v176, 0xf0, v0
	s_addc_u32 s3, s3, 0
	v_mul_u32_u24_e32 v6, 0x5800, v12
	v_add_u32_e32 v6, v6, v176
	s_mul_i32 s6, s5, 0x5800
	s_lshl_b32 s7, s4, 8
	s_add_u32 s8, s6, s7
	s_add_u32 s8, s8, 0x800
	s_lshl_b32 s7, s4, 9
	s_add_u32 s6, s6, s7
	s_add_u32 s6, s6, 0x1000
	s_add_u32 s94, s0, s8
	s_addc_u32 s8, s1, 0
	s_mov_b32 s4, s94
	s_mov_b32 s5, s8
	s_add_u32 s6, s0, s6
	s_addc_u32 s7, s1, 0
	global_load_dwordx4 v[16:19], v6, s[4:5]
	v_add_u32_e32 v6, 0xb0000, v6
	global_load_dwordx4 v[20:23], v6, s[4:5]
	v_add_u32_e32 v6, 0xb0000, v6
	global_load_dwordx4 v[24:27], v6, s[4:5]
	v_add_u32_e32 v6, 0xb0000, v6
	global_load_dwordx4 v[28:31], v6, s[4:5]
	v_lshrrev_b32_e32 v8, 5, v73
	v_and_b32_e32 v9, 31, v73
	v_mul_u32_u24_e32 v6, 0x5800, v8
	v_lshl_add_u32 v6, v9, 4, v6
	global_load_dwordx4 v[32:35], v6, s[6:7]
	v_add_u32_e32 v6, 0x58000, v6
	global_load_dwordx4 v[36:39], v6, s[6:7]
	v_add_u32_e32 v6, 0x58000, v6
	global_load_dwordx4 v[40:43], v6, s[6:7]
	v_add_u32_e32 v6, 0x58000, v6
	global_load_dwordx4 v[44:47], v6, s[6:7]
	v_add_u32_e32 v6, 0x58000, v6
	global_load_dwordx4 v[48:51], v6, s[6:7]
	v_add_u32_e32 v6, 0x58000, v6
	global_load_dwordx4 v[52:55], v6, s[6:7]
	v_add_u32_e32 v6, 0x58000, v6
	global_load_dwordx4 v[56:59], v6, s[6:7]
	v_add_u32_e32 v6, 0x58000, v6
	global_load_dwordx4 v[60:63], v6, s[6:7]
	v_mul_u32_u24_e32 v13, 0x140, v12
	v_add_u32_e32 v13, v13, v176
	v_mul_u32_u24_e32 v14, 0x240, v8
	v_lshl_add_u32 v14, v9, 4, v14
	v_add_u32_e32 v14, 0xa000, v14
	v_sub_u32_e32 v8, 127, v12
	v_cvt_f32_i32_e32 v8, v8
	v_mul_f32_e32 v8, v7, v8
	v_mul_f32_e32 v8, 0x3fb8aa3b, v8
	v_exp_f32_e32 v8, v8
	s_waitcnt vmcnt(11)
	v_lshlrev_b32_e32 v10, 16, v16
	v_and_b32_e32 v11, 0xffff0000, v16
	v_mul_f32_e32 v10, v8, v10
	v_mul_f32_e32 v11, v8, v11
	v_cvt_pk_bf16_f32 v16, v10, v11
	v_lshlrev_b32_e32 v10, 16, v17
	v_and_b32_e32 v11, 0xffff0000, v17
	v_mul_f32_e32 v10, v8, v10
	v_mul_f32_e32 v11, v8, v11
	v_cvt_pk_bf16_f32 v17, v10, v11
	v_lshlrev_b32_e32 v10, 16, v18
	v_and_b32_e32 v11, 0xffff0000, v18
	v_mul_f32_e32 v10, v8, v10
	v_mul_f32_e32 v11, v8, v11
	v_cvt_pk_bf16_f32 v18, v10, v11
	v_lshlrev_b32_e32 v10, 16, v19
	v_and_b32_e32 v11, 0xffff0000, v19
	v_mul_f32_e32 v10, v8, v10
	v_mul_f32_e32 v11, v8, v11
	v_cvt_pk_bf16_f32 v19, v10, v11
	ds_write_b128 v13, v[16:19]
	v_sub_u32_e32 v8, 95, v12
	v_cvt_f32_i32_e32 v8, v8
	v_mul_f32_e32 v8, v7, v8
	v_mul_f32_e32 v8, 0x3fb8aa3b, v8
	v_exp_f32_e32 v8, v8
	s_waitcnt vmcnt(10)
	v_lshlrev_b32_e32 v10, 16, v20
	v_and_b32_e32 v11, 0xffff0000, v20
	v_mul_f32_e32 v10, v8, v10
	v_mul_f32_e32 v11, v8, v11
	v_cvt_pk_bf16_f32 v20, v10, v11
	v_lshlrev_b32_e32 v10, 16, v21
	v_and_b32_e32 v11, 0xffff0000, v21
	v_mul_f32_e32 v10, v8, v10
	v_mul_f32_e32 v11, v8, v11
	v_cvt_pk_bf16_f32 v21, v10, v11
	v_lshlrev_b32_e32 v10, 16, v22
	v_and_b32_e32 v11, 0xffff0000, v22
	v_mul_f32_e32 v10, v8, v10
	v_mul_f32_e32 v11, v8, v11
	v_cvt_pk_bf16_f32 v22, v10, v11
	v_lshlrev_b32_e32 v10, 16, v23
	v_and_b32_e32 v11, 0xffff0000, v23
	v_mul_f32_e32 v10, v8, v10
	v_mul_f32_e32 v11, v8, v11
	v_cvt_pk_bf16_f32 v23, v10, v11
	ds_write_b128 v13, v[20:23] offset:10240
	v_sub_u32_e32 v8, 63, v12
	v_cvt_f32_i32_e32 v8, v8
	v_mul_f32_e32 v8, v7, v8
	v_mul_f32_e32 v8, 0x3fb8aa3b, v8
	v_exp_f32_e32 v8, v8
	s_waitcnt vmcnt(9)
	v_lshlrev_b32_e32 v10, 16, v24
	v_and_b32_e32 v11, 0xffff0000, v24
	v_mul_f32_e32 v10, v8, v10
	v_mul_f32_e32 v11, v8, v11
	v_cvt_pk_bf16_f32 v24, v10, v11
	v_lshlrev_b32_e32 v10, 16, v25
	v_and_b32_e32 v11, 0xffff0000, v25
	v_mul_f32_e32 v10, v8, v10
	v_mul_f32_e32 v11, v8, v11
	v_cvt_pk_bf16_f32 v25, v10, v11
	v_lshlrev_b32_e32 v10, 16, v26
	v_and_b32_e32 v11, 0xffff0000, v26
	v_mul_f32_e32 v10, v8, v10
	v_mul_f32_e32 v11, v8, v11
	v_cvt_pk_bf16_f32 v26, v10, v11
	v_lshlrev_b32_e32 v10, 16, v27
	v_and_b32_e32 v11, 0xffff0000, v27
	v_mul_f32_e32 v10, v8, v10
	v_mul_f32_e32 v11, v8, v11
	v_cvt_pk_bf16_f32 v27, v10, v11
	ds_write_b128 v13, v[24:27] offset:20480
	v_sub_u32_e32 v8, 31, v12
	v_cvt_f32_i32_e32 v8, v8
	v_mul_f32_e32 v8, v7, v8
	v_mul_f32_e32 v8, 0x3fb8aa3b, v8
	v_exp_f32_e32 v8, v8
	s_waitcnt vmcnt(8)
	v_lshlrev_b32_e32 v10, 16, v28
	v_and_b32_e32 v11, 0xffff0000, v28
	v_mul_f32_e32 v10, v8, v10
	v_mul_f32_e32 v11, v8, v11
	v_cvt_pk_bf16_f32 v28, v10, v11
	v_lshlrev_b32_e32 v10, 16, v29
	v_and_b32_e32 v11, 0xffff0000, v29
	v_mul_f32_e32 v10, v8, v10
	v_mul_f32_e32 v11, v8, v11
	v_cvt_pk_bf16_f32 v29, v10, v11
	v_lshlrev_b32_e32 v10, 16, v30
	v_and_b32_e32 v11, 0xffff0000, v30
	v_mul_f32_e32 v10, v8, v10
	v_mul_f32_e32 v11, v8, v11
	v_cvt_pk_bf16_f32 v30, v10, v11
	v_lshlrev_b32_e32 v10, 16, v31
	v_and_b32_e32 v11, 0xffff0000, v31
	v_mul_f32_e32 v10, v8, v10
	v_mul_f32_e32 v11, v8, v11
	v_cvt_pk_bf16_f32 v31, v10, v11
	ds_write_b128 v13, v[28:31] offset:30720
	s_waitcnt vmcnt(7)
	ds_write_b128 v14, v[32:35]
	s_waitcnt vmcnt(6)
	ds_write_b128 v14, v[36:39] offset:9216
	s_waitcnt vmcnt(5)
	ds_write_b128 v14, v[40:43] offset:18432
	s_waitcnt vmcnt(4)
	ds_write_b128 v14, v[44:47] offset:27648
	s_waitcnt vmcnt(3)
	ds_write_b128 v14, v[48:51] offset:36864
	s_waitcnt vmcnt(2)
	ds_write_b128 v14, v[52:55] offset:46080
	s_waitcnt vmcnt(1)
	ds_write_b128 v14, v[56:59] offset:55296
	s_waitcnt vmcnt(0)
	ds_write_b128 v14, v[60:63] offset:64512
	v_bfe_u32 v74, v73, 5, 1
	v_lshlrev_b32_e32 v176, 1, v72
	v_bfe_u32 v0, v73, 2, 2
	v_lshlrev_b32_e32 v2, 1, v73
	v_lshlrev_b32_e32 v3, 3, v73
	v_and_b32_e32 v1, 0xffffffc0, v73
	v_and_b32_e32 v2, 32, v2
	v_and_b32_e32 v3, 24, v3
	v_lshl_or_b32 v5, v74, 3, v0
	v_add3_u32 v1, 0, v2, v1
	v_or_b32_e32 v4, v3, v2
	v_mul_u32_u24_e32 v0, 0x240, v5
	v_mul_u32_u24_e32 v5, 0x140, v5
	v_add3_u32 v68, v1, v3, v0
	v_add3_u32 v70, 0, v5, v4
	s_waitcnt lgkmcnt(0)
	s_barrier
	ds_read_b64_tr_b16 v[0:1], v68 offset:40960
	ds_read_b64_tr_b16 v[2:3], v68 offset:43264
	ds_read_b64_tr_b16 v[4:5], v70
	ds_read_b64_tr_b16 v[6:7], v70 offset:1280
	s_waitcnt lgkmcnt(0)
	v_mfma_f32_32x32x16_bf16 v[48:63], v[0:3], v[4:7], 0
	ds_read_b64_tr_b16 v[4:5], v70 offset:64
	ds_read_b64_tr_b16 v[6:7], v70 offset:1344
	v_add_u32_e32 v69, 0x2400, v68
	v_add_u32_e32 v71, 0x4800, v68
	v_add_u32_e32 v75, 0x6c00, v68
	s_waitcnt lgkmcnt(0)
	v_mfma_f32_32x32x16_bf16 v[32:47], v[0:3], v[4:7], 0
	ds_read_b64_tr_b16 v[4:5], v70 offset:128
	ds_read_b64_tr_b16 v[6:7], v70 offset:1408
	s_waitcnt lgkmcnt(0)
	v_mfma_f32_32x32x16_bf16 v[16:31], v[0:3], v[4:7], 0
	ds_read_b64_tr_b16 v[4:5], v70 offset:192
	ds_read_b64_tr_b16 v[6:7], v70 offset:1472
	ds_read_b64_tr_b16 v[64:65], v68 offset:50176
	ds_read_b64_tr_b16 v[66:67], v68 offset:52480
	ds_read_b64_tr_b16 v[76:77], v70 offset:5120
	ds_read_b64_tr_b16 v[78:79], v70 offset:6400
	s_waitcnt lgkmcnt(0)
	v_mfma_f32_32x32x16_bf16 v[48:63], v[64:67], v[76:79], v[48:63]
	ds_read_b64_tr_b16 v[76:77], v70 offset:5184
	ds_read_b64_tr_b16 v[78:79], v70 offset:6464
	s_waitcnt lgkmcnt(0)
	v_mfma_f32_32x32x16_bf16 v[32:47], v[64:67], v[76:79], v[32:47]
	ds_read_b64_tr_b16 v[76:77], v70 offset:5248
	ds_read_b64_tr_b16 v[78:79], v70 offset:6528
	v_mfma_f32_32x32x16_bf16 v[0:15], v[0:3], v[4:7], 0
	s_waitcnt lgkmcnt(0)
	v_mfma_f32_32x32x16_bf16 v[16:31], v[64:67], v[76:79], v[16:31]
	ds_read_b64_tr_b16 v[76:77], v70 offset:5312
	ds_read_b64_tr_b16 v[78:79], v70 offset:6592
	s_waitcnt lgkmcnt(0)
	v_mfma_f32_32x32x16_bf16 v[0:15], v[64:67], v[76:79], v[0:15]
	ds_read_b64_tr_b16 v[64:65], v68 offset:59392
	ds_read_b64_tr_b16 v[66:67], v68 offset:61696
	ds_read_b64_tr_b16 v[76:77], v70 offset:10240
	ds_read_b64_tr_b16 v[78:79], v70 offset:11520
	s_waitcnt lgkmcnt(0)
	v_mfma_f32_32x32x16_bf16 v[48:63], v[64:67], v[76:79], v[48:63]
	ds_read_b64_tr_b16 v[76:77], v70 offset:10304
	ds_read_b64_tr_b16 v[78:79], v70 offset:11584
	s_waitcnt lgkmcnt(0)
	v_mfma_f32_32x32x16_bf16 v[32:47], v[64:67], v[76:79], v[32:47]
	ds_read_b64_tr_b16 v[76:77], v70 offset:10368
	ds_read_b64_tr_b16 v[78:79], v70 offset:11648
	s_waitcnt lgkmcnt(0)
	v_mfma_f32_32x32x16_bf16 v[16:31], v[64:67], v[76:79], v[16:31]
	ds_read_b64_tr_b16 v[76:77], v70 offset:10432
	ds_read_b64_tr_b16 v[78:79], v70 offset:11712
	s_waitcnt lgkmcnt(0)
	v_mfma_f32_32x32x16_bf16 v[0:15], v[64:67], v[76:79], v[0:15]
	ds_read_b64_tr_b16 v[64:65], v69 offset:59392
	ds_read_b64_tr_b16 v[66:67], v69 offset:61696
	ds_read_b64_tr_b16 v[76:77], v70 offset:15360
	ds_read_b64_tr_b16 v[78:79], v70 offset:16640
	v_add_u32_e32 v69, 0x9000, v68
	v_add_u32_e32 v68, 0xb400, v68
	s_waitcnt lgkmcnt(0)
	v_mfma_f32_32x32x16_bf16 v[48:63], v[64:67], v[76:79], v[48:63]
	ds_read_b64_tr_b16 v[76:77], v70 offset:15424
	ds_read_b64_tr_b16 v[78:79], v70 offset:16704
	s_waitcnt lgkmcnt(0)
	v_mfma_f32_32x32x16_bf16 v[32:47], v[64:67], v[76:79], v[32:47]
	ds_read_b64_tr_b16 v[76:77], v70 offset:15488
	ds_read_b64_tr_b16 v[78:79], v70 offset:16768
	s_waitcnt lgkmcnt(0)
	v_mfma_f32_32x32x16_bf16 v[16:31], v[64:67], v[76:79], v[16:31]
	ds_read_b64_tr_b16 v[76:77], v70 offset:15552
	ds_read_b64_tr_b16 v[78:79], v70 offset:16832
	s_waitcnt lgkmcnt(0)
	v_mfma_f32_32x32x16_bf16 v[0:15], v[64:67], v[76:79], v[0:15]
	ds_read_b64_tr_b16 v[64:65], v71 offset:59392
	ds_read_b64_tr_b16 v[66:67], v71 offset:61696
	ds_read_b64_tr_b16 v[76:77], v70 offset:20480
	ds_read_b64_tr_b16 v[78:79], v70 offset:21760
	s_waitcnt lgkmcnt(0)
	v_mfma_f32_32x32x16_bf16 v[48:63], v[64:67], v[76:79], v[48:63]
	ds_read_b64_tr_b16 v[76:77], v70 offset:20544
	ds_read_b64_tr_b16 v[78:79], v70 offset:21824
	s_waitcnt lgkmcnt(0)
	v_mfma_f32_32x32x16_bf16 v[32:47], v[64:67], v[76:79], v[32:47]
	ds_read_b64_tr_b16 v[76:77], v70 offset:20608
	ds_read_b64_tr_b16 v[78:79], v70 offset:21888
	s_waitcnt lgkmcnt(0)
	v_mfma_f32_32x32x16_bf16 v[16:31], v[64:67], v[76:79], v[16:31]
	ds_read_b64_tr_b16 v[76:77], v70 offset:20672
	ds_read_b64_tr_b16 v[78:79], v70 offset:21952
	s_waitcnt lgkmcnt(0)
	v_mfma_f32_32x32x16_bf16 v[0:15], v[64:67], v[76:79], v[0:15]
	ds_read_b64_tr_b16 v[64:65], v75 offset:59392
	ds_read_b64_tr_b16 v[66:67], v75 offset:61696
	ds_read_b64_tr_b16 v[76:77], v70 offset:25600
	ds_read_b64_tr_b16 v[78:79], v70 offset:26880
	s_waitcnt lgkmcnt(0)
	v_mfma_f32_32x32x16_bf16 v[48:63], v[64:67], v[76:79], v[48:63]
	ds_read_b64_tr_b16 v[76:77], v70 offset:25664
	ds_read_b64_tr_b16 v[78:79], v70 offset:26944
	s_waitcnt lgkmcnt(0)
	v_mfma_f32_32x32x16_bf16 v[32:47], v[64:67], v[76:79], v[32:47]
	ds_read_b64_tr_b16 v[76:77], v70 offset:25728
	ds_read_b64_tr_b16 v[78:79], v70 offset:27008
	s_waitcnt lgkmcnt(0)
	v_mfma_f32_32x32x16_bf16 v[16:31], v[64:67], v[76:79], v[16:31]
	ds_read_b64_tr_b16 v[76:77], v70 offset:25792
	ds_read_b64_tr_b16 v[78:79], v70 offset:27072
	s_waitcnt lgkmcnt(0)
	v_mfma_f32_32x32x16_bf16 v[0:15], v[64:67], v[76:79], v[0:15]
	ds_read_b64_tr_b16 v[64:65], v69 offset:59392
	ds_read_b64_tr_b16 v[66:67], v69 offset:61696
	ds_read_b64_tr_b16 v[76:77], v70 offset:30720
	ds_read_b64_tr_b16 v[78:79], v70 offset:32000
	s_waitcnt lgkmcnt(0)
	v_mfma_f32_32x32x16_bf16 v[48:63], v[64:67], v[76:79], v[48:63]
	ds_read_b64_tr_b16 v[76:77], v70 offset:30784
	ds_read_b64_tr_b16 v[78:79], v70 offset:32064
	s_waitcnt lgkmcnt(0)
	v_mfma_f32_32x32x16_bf16 v[32:47], v[64:67], v[76:79], v[32:47]
	ds_read_b64_tr_b16 v[76:77], v70 offset:30848
	ds_read_b64_tr_b16 v[78:79], v70 offset:32128
	s_waitcnt lgkmcnt(0)
	v_mfma_f32_32x32x16_bf16 v[16:31], v[64:67], v[76:79], v[16:31]
	ds_read_b64_tr_b16 v[76:77], v70 offset:30912
	ds_read_b64_tr_b16 v[78:79], v70 offset:32192
	s_waitcnt lgkmcnt(0)
	v_mfma_f32_32x32x16_bf16 v[0:15], v[64:67], v[76:79], v[0:15]
	ds_read_b64_tr_b16 v[64:65], v68 offset:59392
	ds_read_b64_tr_b16 v[66:67], v68 offset:61696
	ds_read_b64_tr_b16 v[76:77], v70 offset:35840
	ds_read_b64_tr_b16 v[78:79], v70 offset:37120
	s_waitcnt lgkmcnt(0)
	v_mfma_f32_32x32x16_bf16 v[48:63], v[64:67], v[76:79], v[48:63]
	ds_read_b64_tr_b16 v[76:77], v70 offset:35904
	ds_read_b64_tr_b16 v[78:79], v70 offset:37184
	s_waitcnt lgkmcnt(0)
	v_mfma_f32_32x32x16_bf16 v[32:47], v[64:67], v[76:79], v[32:47]
	ds_read_b64_tr_b16 v[76:77], v70 offset:35968
	ds_read_b64_tr_b16 v[78:79], v70 offset:37248
	ds_read_b64_tr_b16 v[68:69], v70 offset:36032
	ds_read_b64_tr_b16 v[70:71], v70 offset:37312
	s_nop 3
	v_cvt_pk_bf16_f32 v48, v48, s0
	v_cvt_pk_bf16_f32 v50, v50, s0
	v_cvt_pk_bf16_f32 v52, v52, s0
	v_cvt_pk_bf16_f32 v54, v54, s0
	v_cvt_pk_bf16_f32 v56, v56, s0
	s_waitcnt lgkmcnt(2)
	v_mfma_f32_32x32x16_bf16 v[16:31], v[64:67], v[76:79], v[16:31]
	v_cvt_pk_bf16_f32 v32, v32, s0
	v_cvt_pk_bf16_f32 v58, v58, s0
	v_cvt_pk_bf16_f32 v60, v60, s0
	v_cvt_pk_bf16_f32 v62, v62, s0
	s_waitcnt lgkmcnt(0)
	v_mfma_f32_32x32x16_bf16 v[0:15], v[64:67], v[68:71], v[0:15]
	v_ashrrev_i32_e32 v64, 1, v73
	v_and_b32_e32 v64, 0xffffffe0, v64
	v_lshl_or_b32 v64, v74, 2, v64
	v_ashrrev_i32_e32 v65, 31, v64
	v_lshl_add_u64 v[66:67], s[2:3], 0, v[176:177]
	v_lshlrev_b64 v[68:69], 8, v[64:65]
	v_lshl_add_u64 v[68:69], v[66:67], 0, v[68:69]
	v_or_b32_e32 v70, 2, v64
	global_store_short v[68:69], v48, off
	v_or_b32_e32 v48, 1, v64
	v_ashrrev_i32_e32 v71, 31, v70
	v_cvt_pk_bf16_f32 v65, v49, s0
	v_ashrrev_i32_e32 v49, 31, v48
	v_lshlrev_b64 v[70:71], 8, v[70:71]
	v_lshlrev_b64 v[48:49], 8, v[48:49]
	v_lshl_add_u64 v[70:71], v[66:67], 0, v[70:71]
	v_or_b32_e32 v72, 8, v64
	v_lshl_add_u64 v[48:49], v[66:67], 0, v[48:49]
	global_store_short v[70:71], v50, off
	v_or_b32_e32 v50, 3, v64
	v_ashrrev_i32_e32 v73, 31, v72
	global_store_short v[48:49], v65, off
	v_cvt_pk_bf16_f32 v65, v51, s0
	v_ashrrev_i32_e32 v51, 31, v50
	v_lshlrev_b64 v[72:73], 8, v[72:73]
	v_lshlrev_b64 v[50:51], 8, v[50:51]
	v_lshl_add_u64 v[72:73], v[66:67], 0, v[72:73]
	v_or_b32_e32 v74, 10, v64
	v_lshl_add_u64 v[50:51], v[66:67], 0, v[50:51]
	global_store_short v[72:73], v52, off
	v_or_b32_e32 v52, 9, v64
	v_ashrrev_i32_e32 v75, 31, v74
	global_store_short v[50:51], v65, off
	v_cvt_pk_bf16_f32 v65, v53, s0
	v_ashrrev_i32_e32 v53, 31, v52
	v_lshlrev_b64 v[74:75], 8, v[74:75]
	v_lshlrev_b64 v[52:53], 8, v[52:53]
	v_lshl_add_u64 v[74:75], v[66:67], 0, v[74:75]
	v_or_b32_e32 v76, 16, v64
	v_lshl_add_u64 v[52:53], v[66:67], 0, v[52:53]
	global_store_short v[74:75], v54, off
	v_or_b32_e32 v54, 11, v64
	v_ashrrev_i32_e32 v77, 31, v76
	v_cvt_pk_bf16_f32 v16, v16, s0
	v_cvt_pk_bf16_f32 v0, v0, s0
	global_store_short v[52:53], v65, off
	v_cvt_pk_bf16_f32 v65, v55, s0
	v_ashrrev_i32_e32 v55, 31, v54
	v_lshlrev_b64 v[76:77], 8, v[76:77]
	global_store_short v[68:69], v32, off offset:64
	v_cvt_pk_bf16_f32 v32, v33, s0
	global_store_short v[68:69], v16, off offset:128
	v_cvt_pk_bf16_f32 v16, v17, s0
	global_store_short v[68:69], v0, off offset:192
	v_cvt_pk_bf16_f32 v0, v1, s0
	v_lshlrev_b64 v[54:55], 8, v[54:55]
	v_lshl_add_u64 v[76:77], v[66:67], 0, v[76:77]
	v_or_b32_e32 v78, 18, v64
	global_store_short v[48:49], v32, off offset:64
	v_cvt_pk_bf16_f32 v32, v34, s0
	global_store_short v[48:49], v16, off offset:128
	v_cvt_pk_bf16_f32 v16, v18, s0
	global_store_short v[48:49], v0, off offset:192
	v_cvt_pk_bf16_f32 v0, v2, s0
	v_lshl_add_u64 v[54:55], v[66:67], 0, v[54:55]
	global_store_short v[76:77], v56, off
	v_or_b32_e32 v56, 17, v64
	v_ashrrev_i32_e32 v79, 31, v78
	global_store_short v[70:71], v32, off offset:64
	v_cvt_pk_bf16_f32 v32, v35, s0
	global_store_short v[70:71], v16, off offset:128
	v_cvt_pk_bf16_f32 v16, v19, s0
	global_store_short v[70:71], v0, off offset:192
	v_cvt_pk_bf16_f32 v0, v3, s0
	global_store_short v[54:55], v65, off
	v_cvt_pk_bf16_f32 v65, v57, s0
	v_ashrrev_i32_e32 v57, 31, v56
	v_lshlrev_b64 v[78:79], 8, v[78:79]
	global_store_short v[50:51], v32, off offset:64
	v_cvt_pk_bf16_f32 v32, v36, s0
	global_store_short v[50:51], v16, off offset:128
	v_cvt_pk_bf16_f32 v16, v20, s0
	global_store_short v[50:51], v0, off offset:192
	v_cvt_pk_bf16_f32 v0, v4, s0
	v_lshlrev_b64 v[56:57], 8, v[56:57]
	v_lshl_add_u64 v[78:79], v[66:67], 0, v[78:79]
	v_or_b32_e32 v80, 24, v64
	global_store_short v[72:73], v32, off offset:64
	v_cvt_pk_bf16_f32 v32, v37, s0
	global_store_short v[72:73], v16, off offset:128
	v_cvt_pk_bf16_f32 v16, v21, s0
	global_store_short v[72:73], v0, off offset:192
	v_cvt_pk_bf16_f32 v0, v5, s0
	v_lshl_add_u64 v[56:57], v[66:67], 0, v[56:57]
	global_store_short v[78:79], v58, off
	v_or_b32_e32 v58, 19, v64
	v_ashrrev_i32_e32 v81, 31, v80
	global_store_short v[52:53], v32, off offset:64
	v_cvt_pk_bf16_f32 v32, v38, s0
	global_store_short v[52:53], v16, off offset:128
	v_cvt_pk_bf16_f32 v16, v22, s0
	global_store_short v[52:53], v0, off offset:192
	v_cvt_pk_bf16_f32 v0, v6, s0
	global_store_short v[56:57], v65, off
	v_cvt_pk_bf16_f32 v65, v59, s0
	v_ashrrev_i32_e32 v59, 31, v58
	v_lshlrev_b64 v[80:81], 8, v[80:81]
	global_store_short v[74:75], v32, off offset:64
	v_cvt_pk_bf16_f32 v32, v39, s0
	global_store_short v[74:75], v16, off offset:128
	v_cvt_pk_bf16_f32 v16, v23, s0
	global_store_short v[74:75], v0, off offset:192
	v_cvt_pk_bf16_f32 v0, v7, s0
	v_lshlrev_b64 v[58:59], 8, v[58:59]
	v_lshl_add_u64 v[80:81], v[66:67], 0, v[80:81]
	v_or_b32_e32 v82, 26, v64
	global_store_short v[54:55], v32, off offset:64
	v_cvt_pk_bf16_f32 v32, v40, s0
	global_store_short v[54:55], v16, off offset:128
	v_cvt_pk_bf16_f32 v16, v24, s0
	global_store_short v[54:55], v0, off offset:192
	v_cvt_pk_bf16_f32 v0, v8, s0
	v_lshl_add_u64 v[58:59], v[66:67], 0, v[58:59]
	global_store_short v[80:81], v60, off
	v_or_b32_e32 v60, 25, v64
	v_ashrrev_i32_e32 v83, 31, v82
	global_store_short v[76:77], v32, off offset:64
	v_cvt_pk_bf16_f32 v32, v41, s0
	global_store_short v[76:77], v16, off offset:128
	v_cvt_pk_bf16_f32 v16, v25, s0
	global_store_short v[76:77], v0, off offset:192
	v_cvt_pk_bf16_f32 v0, v9, s0
	global_store_short v[58:59], v65, off
	v_cvt_pk_bf16_f32 v65, v61, s0
	v_ashrrev_i32_e32 v61, 31, v60
	v_lshlrev_b64 v[82:83], 8, v[82:83]
	global_store_short v[56:57], v32, off offset:64
	v_cvt_pk_bf16_f32 v32, v42, s0
	global_store_short v[56:57], v16, off offset:128
	v_cvt_pk_bf16_f32 v16, v26, s0
	global_store_short v[56:57], v0, off offset:192
	v_cvt_pk_bf16_f32 v0, v10, s0
	v_lshlrev_b64 v[60:61], 8, v[60:61]
	v_lshl_add_u64 v[82:83], v[66:67], 0, v[82:83]
	global_store_short v[78:79], v32, off offset:64
	v_cvt_pk_bf16_f32 v32, v43, s0
	global_store_short v[78:79], v16, off offset:128
	v_cvt_pk_bf16_f32 v16, v27, s0
	global_store_short v[78:79], v0, off offset:192
	v_cvt_pk_bf16_f32 v0, v11, s0
	v_lshl_add_u64 v[60:61], v[66:67], 0, v[60:61]
	global_store_short v[82:83], v62, off
	v_or_b32_e32 v62, 27, v64
	global_store_short v[58:59], v32, off offset:64
	v_cvt_pk_bf16_f32 v32, v44, s0
	global_store_short v[58:59], v16, off offset:128
	v_cvt_pk_bf16_f32 v16, v28, s0
	global_store_short v[58:59], v0, off offset:192
	v_cvt_pk_bf16_f32 v0, v12, s0
	global_store_short v[60:61], v65, off
	v_cvt_pk_bf16_f32 v65, v63, s0
	v_ashrrev_i32_e32 v63, 31, v62
	global_store_short v[80:81], v32, off offset:64
	v_cvt_pk_bf16_f32 v32, v45, s0
	global_store_short v[80:81], v16, off offset:128
	v_cvt_pk_bf16_f32 v16, v29, s0
	global_store_short v[80:81], v0, off offset:192
	v_cvt_pk_bf16_f32 v0, v13, s0
	v_lshlrev_b64 v[62:63], 8, v[62:63]
	global_store_short v[60:61], v32, off offset:64
	v_cvt_pk_bf16_f32 v32, v46, s0
	global_store_short v[60:61], v16, off offset:128
	v_cvt_pk_bf16_f32 v16, v30, s0
	global_store_short v[60:61], v0, off offset:192
	v_cvt_pk_bf16_f32 v0, v14, s0
	v_lshl_add_u64 v[62:63], v[66:67], 0, v[62:63]
	global_store_short v[82:83], v32, off offset:64
	v_cvt_pk_bf16_f32 v32, v47, s0
	global_store_short v[82:83], v16, off offset:128
	v_cvt_pk_bf16_f32 v16, v31, s0
	global_store_short v[82:83], v0, off offset:192
	v_cvt_pk_bf16_f32 v0, v15, s0
	global_store_short v[62:63], v65, off
	global_store_short v[62:63], v32, off offset:64
	global_store_short v[62:63], v16, off offset:128
	global_store_short v[62:63], v0, off offset:192
	s_waitcnt vmcnt(63) expcnt(7) lgkmcnt(15)
	s_barrier

.LBB0_734:
	s_andn2_b64 vcc, exec, s[2:3]
	s_cbranch_vccnz .LBB0_681
	s_ashr_i32 s38, s56, 8
	s_and_b32 s57, s56, 7
	s_bfe_u32 s2, s56, 0x50003
	s_cmp_eq_u32 s38, 1
	s_cselect_b32 s3, 2, 4
	s_cmpk_gt_u32 s56, 0xff
	s_cselect_b32 s4, s3, 0
	s_lshr_b32 s3, 32, s4
	s_add_i32 s3, s3, -1
	s_and_b32 s7, s3, s2
	s_lshl_b32 s6, s7, 8
	v_mov_b32_e32 v1, v208
	s_add_i32 s56, s6, 0xffffff80
	s_sub_i32 s5, 5, s4
	v_and_b32_e32 v0, 15, v1
	v_ashrrev_i32_e32 v4, 4, v1
	v_lshlrev_b32_e32 v2, 3, v0
	v_add_u32_e32 v176, s56, v4
	s_lshr_b32 s94, s2, s5
	s_lshl_b32 s5, s57, 7
	v_lshl_add_u32 v0, v0, 4, 0
	v_lshlrev_b32_e32 v2, 1, v2
	v_ashrrev_i32_e32 v4, 4, v1
	v_lshlrev_b32_e32 v6, s4, v4
	v_mul_u32_u24_e32 v6, 0x5800, v6
	v_add_u32_e32 v6, v6, v2
	v_mad_u32_u24 v5, v4, s44, v0
	v_add_u32_e32 v7, 0xf000, v5
	s_lshl_b32 s8, s56, s4
	s_add_i32 s8, s8, s94
	s_mul_hi_i32 s9, s8, 0x5800
	s_mul_i32 s8, s8, 0x5800
	s_lshl_b32 s2, s5, 1
	s_add_u32 s2, s2, 0x4000
	s_add_u32 s8, s8, s2
	s_addc_u32 s9, s9, 0
	s_add_u32 s8, s8, s0
	s_addc_u32 s9, s9, s1
	s_lshl_b32 s3, 0xb0000, s4
	s_add_i32 s10, s56, 0
	s_cmp_lt_i32 s10, 0
	s_cbranch_scc1 .Ldl_z1
	global_load_dwordx4 v[16:19], v6, s[8:9]
	s_branch .Ldl_l2
.Ldl_z1:
	v_mov_b32_e32 v16, 0
	v_mov_b32_e32 v17, 0
	v_mov_b32_e32 v18, 0
	v_mov_b32_e32 v19, 0
.Ldl_l2:
	v_add_u32_e32 v6, s3, v6
	s_add_i32 s10, s56, 32
	s_cmp_lt_i32 s10, 0
	s_cbranch_scc1 .Ldl_z3
	global_load_dwordx4 v[20:23], v6, s[8:9]
	s_branch .Ldl_l4
.Ldl_z3:
	v_mov_b32_e32 v20, 0
	v_mov_b32_e32 v21, 0
	v_mov_b32_e32 v22, 0
	v_mov_b32_e32 v23, 0
.Ldl_l4:
	v_add_u32_e32 v6, s3, v6
	s_add_i32 s10, s56, 64
	s_cmp_lt_i32 s10, 0
	s_cbranch_scc1 .Ldl_z5
	global_load_dwordx4 v[24:27], v6, s[8:9]
	s_branch .Ldl_l6
.Ldl_z5:
	v_mov_b32_e32 v24, 0
	v_mov_b32_e32 v25, 0
	v_mov_b32_e32 v26, 0
	v_mov_b32_e32 v27, 0
.Ldl_l6:
	v_add_u32_e32 v6, s3, v6
	s_add_i32 s10, s56, 96
	s_cmp_lt_i32 s10, 0
	s_cbranch_scc1 .Ldl_z7
	global_load_dwordx4 v[28:31], v6, s[8:9]
	s_branch .Ldl_l8
.Ldl_z7:
	v_mov_b32_e32 v28, 0
	v_mov_b32_e32 v29, 0
	v_mov_b32_e32 v30, 0
	v_mov_b32_e32 v31, 0
.Ldl_l8:
	v_add_u32_e32 v6, s3, v6
	s_add_i32 s10, s56, 128
	s_cmp_lt_i32 s10, 0
	s_cbranch_scc1 .Ldl_z9
	global_load_dwordx4 v[32:35], v6, s[8:9]
	s_branch .Ldl_l10
.Ldl_z9:
	v_mov_b32_e32 v32, 0
	v_mov_b32_e32 v33, 0
	v_mov_b32_e32 v34, 0
	v_mov_b32_e32 v35, 0
.Ldl_l10:
	v_add_u32_e32 v6, s3, v6
	s_add_i32 s10, s56, 160
	s_cmp_lt_i32 s10, 0
	s_cbranch_scc1 .Ldl_z11
	global_load_dwordx4 v[36:39], v6, s[8:9]
	s_branch .Ldl_l12
.Ldl_z11:
	v_mov_b32_e32 v36, 0
	v_mov_b32_e32 v37, 0
	v_mov_b32_e32 v38, 0
	v_mov_b32_e32 v39, 0
.Ldl_l12:
	v_add_u32_e32 v6, s3, v6
	s_add_i32 s10, s56, 192
	s_cmp_lt_i32 s10, 0
	s_cbranch_scc1 .Ldl_z13
	global_load_dwordx4 v[40:43], v6, s[8:9]
	s_branch .Ldl_l14
.Ldl_z13:
	v_mov_b32_e32 v40, 0
	v_mov_b32_e32 v41, 0
	v_mov_b32_e32 v42, 0
	v_mov_b32_e32 v43, 0
.Ldl_l14:
	v_add_u32_e32 v6, s3, v6
	s_add_i32 s10, s56, 224
	s_cmp_lt_i32 s10, 0
	s_cbranch_scc1 .Ldl_z15
	global_load_dwordx4 v[44:47], v6, s[8:9]
	s_branch .Ldl_l16
.Ldl_z15:
	v_mov_b32_e32 v44, 0
	v_mov_b32_e32 v45, 0
	v_mov_b32_e32 v46, 0
	v_mov_b32_e32 v47, 0
.Ldl_l16:
	v_add_u32_e32 v6, s3, v6
	s_add_i32 s10, s56, 256
	s_cmp_lt_i32 s10, 0
	s_cbranch_scc1 .Ldl_z17
	global_load_dwordx4 v[48:51], v6, s[8:9]
	s_branch .Ldl_l18
.Ldl_z17:
	v_mov_b32_e32 v48, 0
	v_mov_b32_e32 v49, 0
	v_mov_b32_e32 v50, 0
	v_mov_b32_e32 v51, 0
.Ldl_l18:
	v_add_u32_e32 v6, s3, v6
	s_add_i32 s10, s56, 288
	s_cmp_lt_i32 s10, 0
	s_cbranch_scc1 .Ldl_z19
	global_load_dwordx4 v[52:55], v6, s[8:9]
	s_branch .Ldl_l20
.Ldl_z19:
	v_mov_b32_e32 v52, 0
	v_mov_b32_e32 v53, 0
	v_mov_b32_e32 v54, 0
	v_mov_b32_e32 v55, 0
.Ldl_l20:
	v_add_u32_e32 v6, s3, v6
	s_add_i32 s10, s56, 320
	s_cmp_lt_i32 s10, 0
	s_cbranch_scc1 .Ldl_z21
	global_load_dwordx4 v[56:59], v6, s[8:9]
	s_branch .Ldl_l22
.Ldl_z21:
	v_mov_b32_e32 v56, 0
	v_mov_b32_e32 v57, 0
	v_mov_b32_e32 v58, 0
	v_mov_b32_e32 v59, 0
.Ldl_l22:
	v_add_u32_e32 v6, s3, v6
	s_add_i32 s10, s56, 352
	s_cmp_lt_i32 s10, 0
	s_cbranch_scc1 .Ldl_z23
	global_load_dwordx4 v[60:63], v6, s[8:9]
	s_branch .Ldl_l24
.Ldl_z23:
	v_mov_b32_e32 v60, 0
	v_mov_b32_e32 v61, 0
	v_mov_b32_e32 v62, 0
	v_mov_b32_e32 v63, 0
.Ldl_l24:
	s_waitcnt vmcnt(0)
	ds_write_b128 v5, v[16:19]
	ds_write_b128 v5, v[20:23] offset:10240
	ds_write_b128 v5, v[24:27] offset:20480
	ds_write_b128 v5, v[28:31] offset:30720
	ds_write_b128 v5, v[32:35] offset:40960
	ds_write_b128 v5, v[36:39] offset:51200
	ds_write_b128 v7, v[40:43]
	ds_write_b128 v7, v[44:47] offset:10240
	ds_write_b128 v7, v[48:51] offset:20480
	ds_write_b128 v7, v[52:55] offset:30720
	ds_write_b128 v7, v[56:59] offset:40960
	ds_write_b128 v7, v[60:63] offset:51200
	s_cmp_eq_u32 s7, 0
	s_cselect_b64 vcc, -1, 0
	s_ashr_i32 s39, s38, 31
	s_lshl_b64 s[2:3], s[38:39], 24
	v_ashrrev_i32_e32 v181, 6, v1
	s_add_u32 s2, s88, s2
	s_addc_u32 s3, s89, s3
	s_lshl_b32 s7, s57, s4
	v_lshl_add_u32 v2, v181, 5, s6
	s_add_i32 s7, s94, s7
	s_sub_i32 s8, 8, s4
	v_and_or_b32 v2, v1, 31, v2
	s_lshl_b32 s7, s7, s8
	v_ashrrev_i32_e32 v3, 31, v2
	s_lshl_b32 s7, s7, 13
	v_lshlrev_b64 v[2:3], s4, v[2:3]
	s_add_u32 s40, s2, s7
	v_lshl_add_u64 v[182:183], v[2:3], 0, s[94:95]
	v_mov_b64_e32 v[2:3], s[0:1]
	s_addc_u32 s41, s3, 0
	v_mad_u64_u32 v[2:3], s[2:3], v182, s55, v[2:3]
	v_sub_u32_e32 v0, 4, v181
	v_bfe_u32 v8, v1, 5, 1
	v_mad_i32_i24 v3, v183, s55, v3
	s_lshl_b32 s94, s5, 1
	v_max_i32_e32 v0, 0, v0
	v_lshl_add_u64 v[2:3], v[2:3], 0, s[94:95]
	v_lshlrev_b32_e32 v176, 4, v8
	v_lshl_add_u64 v[2:3], v[2:3], 0, v[176:177]
	s_mov_b64 s[2:3], 0x3000
	v_cndmask_b32_e32 v192, 0, v0, vcc
	v_lshl_add_u64 v[4:5], v[2:3], 0, s[2:3]
	s_movk_i32 s2, 0x3000
	v_add_u32_e32 v0, v192, v181
	v_add_co_u32_e64 v2, s[2:3], s2, v2
	v_lshlrev_b32_e32 v9, 5, v0
	s_nop 0
	v_addc_co_u32_e64 v3, s[2:3], 0, v3, s[2:3]
	global_load_dwordx4 v[80:83], v[4:5], off offset:32
	global_load_dwordx4 v[84:87], v[4:5], off offset:64
	global_load_dwordx4 v[88:91], v[4:5], off offset:96
	global_load_dwordx4 v[92:95], v[4:5], off offset:128
	global_load_dwordx4 v[96:99], v[4:5], off offset:160
	global_load_dwordx4 v[100:103], v[4:5], off offset:192
	global_load_dwordx4 v[104:107], v[2:3], off
	global_load_dwordx4 v[108:111], v[4:5], off offset:224
	v_add_u32_e32 v2, s56, v9
	v_ashrrev_i32_e32 v2, 5, v2
	v_ashrrev_i32_e32 v3, 31, v2
	v_and_b32_e32 v178, 63, v1
	v_lshlrev_b64 v[2:3], 13, v[2:3]
	v_lshl_add_u64 v[2:3], s[40:41], 0, v[2:3]
	v_lshlrev_b32_e32 v176, 4, v178
	v_lshl_add_u64 v[4:5], v[2:3], 0, v[176:177]
	v_or_b32_e32 v184, 0x1000, v176
	v_mov_b32_e32 v185, v177
	global_load_dwordx4 v[124:127], v[4:5], off
	global_load_dwordx4 v[120:123], v[4:5], off offset:1024
	global_load_dwordx4 v[116:119], v[4:5], off offset:2048
	global_load_dwordx4 v[112:115], v[4:5], off offset:3072
	v_lshl_add_u64 v[4:5], v[2:3], 0, v[184:185]
	v_or_b32_e32 v186, 0x1400, v176
	v_mov_b32_e32 v187, v177
	v_or_b32_e32 v188, 0x1800, v176
	v_mov_b32_e32 v189, v177
	v_lshl_add_u64 v[6:7], v[2:3], 0, v[186:187]
	global_load_dwordx4 v[132:135], v[4:5], off
	global_load_dwordx4 v[128:131], v[6:7], off
	v_lshl_add_u64 v[4:5], v[2:3], 0, v[188:189]
	v_or_b32_e32 v190, 0x1c00, v176
	v_mov_b32_e32 v191, v177
	v_lshl_add_u64 v[2:3], v[2:3], 0, v[190:191]
	global_load_dwordx4 v[140:143], v[4:5], off
	global_load_dwordx4 v[136:139], v[2:3], off
	v_cmp_lt_i32_e32 vcc, v204, v200
	v_lshlrev_b32_e32 v193, 2, v8
	v_lshlrev_b32_e32 v3, 1, v1
	v_cndmask_b32_e32 v2, v197, v204, vcc
	v_lshlrev_b32_e32 v194, 2, v2
	v_bfe_u32 v2, v1, 2, 2
	v_lshlrev_b32_e32 v1, 3, v1
	v_and_b32_e32 v195, 24, v1
	v_or3_b32 v1, v9, v193, v2
	v_and_b32_e32 v3, 32, v3
	v_mul_lo_u32 v1, v1, s44
	v_or_b32_e32 v1, v1, v3
	s_movk_i32 s34, 0x2800
	v_add_u32_e32 v246, 0, v1
	v_mul_lo_u32 v0, v0, s34
	v_mul_u32_u24_e32 v1, 0x500, v8
	s_movk_i32 s2, 0xffdc
	v_or_b32_e32 v0, v0, v1
	v_mad_i32_i24 v230, v8, s2, v178
	v_mad_u32_u24 v0, v2, s44, v0
	v_add_u32_e32 v231, -1, v230
	v_add_u32_e32 v232, -2, v230
	v_add_u32_e32 v233, -3, v230
	v_add_u32_e32 v234, -8, v230
	v_add_u32_e32 v235, -9, v230
	v_add_u32_e32 v236, -10, v230
	v_add_u32_e32 v237, -11, v230
	v_add_u32_e32 v238, -16, v230
	v_subrev_u32_e32 v239, 17, v230
	v_subrev_u32_e32 v240, 18, v230
	v_subrev_u32_e32 v241, 19, v230
	v_subrev_u32_e32 v242, 24, v230
	v_subrev_u32_e32 v243, 25, v230
	v_subrev_u32_e32 v244, 26, v230
	v_subrev_u32_e32 v245, 27, v230
	v_or_b32_e32 v0, v0, v3
	v_mov_b32_e32 v248, 0
	v_cmp_gt_u32_e32 vcc, s59, v230
	v_cmp_gt_u32_e64 s[2:3], s59, v231
	v_cmp_gt_u32_e64 s[4:5], s59, v232
	v_cmp_gt_u32_e64 s[6:7], s59, v233
	v_cmp_gt_u32_e64 s[8:9], s59, v234
	v_cmp_gt_u32_e64 s[10:11], s59, v235
	v_cmp_gt_u32_e64 s[12:13], s59, v236
	v_cmp_gt_u32_e64 s[14:15], s59, v237
	v_cmp_gt_u32_e64 s[16:17], s59, v238
	v_cmp_gt_u32_e64 s[18:19], s59, v239
	v_cmp_gt_u32_e64 s[20:21], s59, v240
	v_cmp_gt_u32_e64 s[22:23], s59, v241
	v_cmp_gt_u32_e64 s[24:25], s59, v242
	v_cmp_gt_u32_e64 s[26:27], s59, v243
	v_cmp_gt_u32_e64 s[28:29], s59, v244
	v_cmp_gt_u32_e64 s[30:31], s59, v245
	v_add_u32_e32 v247, 0, v0
	v_mov_b32_e32 v249, 0xf149f2ca
	s_mov_b64 s[42:43], 0
	v_mov_b32_e32 v0, 0
	v_mov_b32_e32 v1, v248
	v_mov_b32_e32 v2, v248
	v_mov_b32_e32 v3, v248
	v_mov_b32_e32 v4, v248
	v_mov_b32_e32 v5, v248
	v_mov_b32_e32 v6, v248
	v_mov_b32_e32 v7, v248
	v_mov_b32_e32 v8, v248
	v_mov_b32_e32 v9, v248
	v_mov_b32_e32 v10, v248
	v_mov_b32_e32 v11, v248
	v_mov_b32_e32 v12, v248
	v_mov_b32_e32 v13, v248
	v_mov_b32_e32 v14, v248
	v_mov_b32_e32 v15, v248
	v_mov_b32_e32 v16, 0
	v_mov_b32_e32 v17, v248
	v_mov_b32_e32 v18, v248
	v_mov_b32_e32 v19, v248
	v_mov_b32_e32 v20, v248
	v_mov_b32_e32 v21, v248
	v_mov_b32_e32 v22, v248
	v_mov_b32_e32 v23, v248
	v_mov_b32_e32 v24, v248
	v_mov_b32_e32 v25, v248
	v_mov_b32_e32 v26, v248
	v_mov_b32_e32 v27, v248
	v_mov_b32_e32 v28, v248
	v_mov_b32_e32 v29, v248
	v_mov_b32_e32 v30, v248
	v_mov_b32_e32 v31, v248
	v_mov_b32_e32 v32, 0
	v_mov_b32_e32 v33, v248
	v_mov_b32_e32 v34, v248
	v_mov_b32_e32 v35, v248
	v_mov_b32_e32 v36, v248
	v_mov_b32_e32 v37, v248
	v_mov_b32_e32 v38, v248
	v_mov_b32_e32 v39, v248
	v_mov_b32_e32 v40, v248
	v_mov_b32_e32 v41, v248
	v_mov_b32_e32 v42, v248
	v_mov_b32_e32 v43, v248
	v_mov_b32_e32 v44, v248
	v_mov_b32_e32 v45, v248
	v_mov_b32_e32 v46, v248
	v_mov_b32_e32 v47, v248
	v_mov_b32_e32 v48, 0
	v_mov_b32_e32 v49, v248
	v_mov_b32_e32 v50, v248
	v_mov_b32_e32 v51, v248
	v_mov_b32_e32 v52, v248
	v_mov_b32_e32 v53, v248
	v_mov_b32_e32 v54, v248
	v_mov_b32_e32 v55, v248
	v_mov_b32_e32 v56, v248
	v_mov_b32_e32 v57, v248
	v_mov_b32_e32 v58, v248
	v_mov_b32_e32 v59, v248
	v_mov_b32_e32 v60, v248
	v_mov_b32_e32 v61, v248
	v_mov_b32_e32 v62, v248
	v_mov_b32_e32 v63, v248
	s_waitcnt lgkmcnt(0)
	s_barrier
	s_branch .LBB0_762
